# P8: the two w2 fragment loads of each step issued together (were load, wait, MFMA, load, wait, MFMA)
# speedup vs baseline: 1.0034x; 1.0006x over previous
.LBB0_1000:
	v_lshl_add_u64 v[66:67], s[72:73], 0, v[54:55]
	v_add_co_u32_e32 v68, vcc, s60, v66
	v_lshl_add_u64 v[40:41], s[72:73], 0, v[52:53]
	s_nop 0
	v_addc_co_u32_e32 v69, vcc, 0, v67, vcc
	v_add_co_u32_e32 v70, vcc, s61, v40
	v_lshl_add_u64 v[38:39], v[66:67], 0, s[2:3]
	s_nop 0
	v_addc_co_u32_e32 v71, vcc, 0, v41, vcc
	global_load_dwordx4 v[34:37], v[68:69], off
	global_load_dwordx4 v[60:63], v[38:39], off offset:16
	v_lshl_add_u64 v[38:39], v[40:41], 0, s[4:5]
	global_load_dwordx4 v[78:81], v[70:71], off
	global_load_dwordx4 v[82:85], v[38:39], off offset:16
	v_add_co_u32_e32 v64, vcc, s62, v40
	v_lshl_add_u64 v[86:87], v[40:41], 0, s[16:17]
	s_nop 0
	v_addc_co_u32_e32 v65, vcc, 0, v41, vcc
	s_add_i32 s12, s12, -4
	v_lshl_add_u64 v[54:55], v[54:55], 0, s[54:55]
	v_lshl_add_u64 v[52:53], v[52:53], 0, s[54:55]
	s_cmp_eq_u32 s12, 0
	s_waitcnt vmcnt(1)
	v_pk_add_f32 v[38:39], v[36:37], v[80:81]
	s_waitcnt vmcnt(0)
	v_pk_add_f32 v[80:81], v[60:61], v[82:83]
	v_lshl_add_u64 v[60:61], v[40:41], 0, s[6:7]
	v_pk_add_f32 v[72:73], v[34:35], v[78:79]
	v_pk_add_f32 v[78:79], v[62:63], v[84:85]
	global_load_dwordx4 v[34:37], v[64:65], off
	s_nop 0
	global_load_dwordx4 v[60:63], v[60:61], off offset:16
	s_waitcnt vmcnt(1)
	v_pk_add_f32 v[38:39], v[38:39], v[36:37]
	s_waitcnt vmcnt(0)
	v_pk_add_f32 v[82:83], v[78:79], v[62:63]
	v_add_co_u32_e32 v62, vcc, s63, v40
	v_lshl_add_u64 v[78:79], v[40:41], 0, s[8:9]
	s_nop 0
	v_addc_co_u32_e32 v63, vcc, 0, v41, vcc
	v_pk_add_f32 v[72:73], v[72:73], v[34:35]
	v_pk_add_f32 v[60:61], v[80:81], v[60:61]
	global_load_dwordx4 v[34:37], v[62:63], off
	s_nop 0
	global_load_dwordx4 v[78:81], v[78:79], off offset:16
	s_waitcnt vmcnt(1)
	v_pk_add_f32 v[38:39], v[38:39], v[36:37]
	s_waitcnt vmcnt(0)
	v_pk_add_f32 v[84:85], v[60:61], v[78:79]
	v_add_co_u32_e32 v60, vcc, s64, v40
	v_lshl_add_u64 v[78:79], v[40:41], 0, s[10:11]
	s_nop 0
	v_addc_co_u32_e32 v61, vcc, 0, v41, vcc
	v_pk_add_f32 v[72:73], v[72:73], v[34:35]
	v_pk_add_f32 v[82:83], v[82:83], v[80:81]
	global_load_dwordx4 v[34:37], v[60:61], off
	s_nop 0
	global_load_dwordx4 v[78:81], v[78:79], off offset:16
	s_waitcnt vmcnt(1)
	v_pk_add_f32 v[34:35], v[72:73], v[34:35]
	s_nop 0
	v_mul_f32_e32 v49, 0x3d372713, v34
	v_mul_f32_e32 v49, v34, v49
	v_fma_f32 v49, v34, v49, v34
	v_mul_f32_e32 v49, 0x3fcc422a, v49
	s_waitcnt vmcnt(0)
	v_pk_add_f32 v[72:73], v[84:85], v[78:79]
	v_mul_f32_e32 v49, 0xbfb8aa3b, v49
	v_exp_f32_e32 v78, v49
	v_mul_f32_e32 v49, 0x3d372713, v72
	v_mul_f32_e32 v49, v72, v49
	v_fma_f32 v49, v72, v49, v72
	v_mul_f32_e32 v49, 0x3fcc422a, v49
	v_mul_f32_e32 v49, 0xbfb8aa3b, v49
	v_pk_add_f32 v[36:37], v[38:39], v[36:37]
	v_pk_add_f32 v[38:39], v[82:83], v[80:81]
	v_exp_f32_e32 v80, v49
	v_mul_f32_e32 v49, 0x3d372713, v35
	v_mul_f32_e32 v49, v35, v49
	v_fma_f32 v49, v35, v49, v35
	v_mul_f32_e32 v49, 0x3fcc422a, v49
	v_mul_f32_e32 v49, 0xbfb8aa3b, v49
	v_exp_f32_e32 v79, v49
	s_nop 0
	v_pk_add_f32 v[78:79], v[78:79], 1.0 op_sel_hi:[1,0]
	s_nop 0
	v_div_scale_f32 v49, s[66:67], v79, v79, 1.0
	v_rcp_f32_e32 v77, v49
	s_nop 0
	v_fma_f32 v81, -v49, v77, 1.0
	v_fmac_f32_e32 v77, v81, v77
	v_div_scale_f32 v81, vcc, 1.0, v79, 1.0
	v_mul_f32_e32 v82, v81, v77
	v_fma_f32 v83, -v49, v82, v81
	v_fmac_f32_e32 v82, v83, v77
	v_fma_f32 v49, -v49, v82, v81
	v_div_fmas_f32 v49, v49, v77, v82
	v_div_fixup_f32 v79, v49, v79, 1.0
	v_div_scale_f32 v49, s[66:67], v78, v78, 1.0
	v_rcp_f32_e32 v77, v49
	s_nop 0
	v_fma_f32 v81, -v49, v77, 1.0
	v_fmac_f32_e32 v77, v81, v77
	v_div_scale_f32 v81, vcc, 1.0, v78, 1.0
	v_mul_f32_e32 v82, v81, v77
	v_fma_f32 v83, -v49, v82, v81
	v_fmac_f32_e32 v82, v83, v77
	v_fma_f32 v49, -v49, v82, v81
	v_div_fmas_f32 v49, v49, v77, v82
	v_div_fixup_f32 v78, v49, v78, 1.0
	v_mul_f32_e32 v49, 0x3d372713, v73
	v_mul_f32_e32 v49, v73, v49
	v_fma_f32 v49, v73, v49, v73
	v_mul_f32_e32 v49, 0x3fcc422a, v49
	v_mul_f32_e32 v49, 0xbfb8aa3b, v49
	v_exp_f32_e32 v81, v49
	v_pk_mul_f32 v[34:35], v[34:35], v[78:79]
	v_pk_add_f32 v[78:79], v[80:81], 1.0 op_sel_hi:[1,0]
	s_nop 0
	v_div_scale_f32 v49, s[66:67], v79, v79, 1.0
	v_rcp_f32_e32 v77, v49
	v_cvt_pk_bf16_f32 v34, v34, v35
	v_fma_f32 v80, -v49, v77, 1.0
	v_fmac_f32_e32 v77, v80, v77
	v_div_scale_f32 v80, vcc, 1.0, v79, 1.0
	v_mul_f32_e32 v81, v80, v77
	v_fma_f32 v82, -v49, v81, v80
	v_fmac_f32_e32 v81, v82, v77
	v_fma_f32 v49, -v49, v81, v80
	v_div_fmas_f32 v49, v49, v77, v81
	v_div_fixup_f32 v79, v49, v79, 1.0
	v_div_scale_f32 v49, s[66:67], v78, v78, 1.0
	v_rcp_f32_e32 v77, v49
	s_nop 0
	v_fma_f32 v80, -v49, v77, 1.0
	v_fmac_f32_e32 v77, v80, v77
	v_div_scale_f32 v80, vcc, 1.0, v78, 1.0
	v_mul_f32_e32 v81, v80, v77
	v_fma_f32 v82, -v49, v81, v80
	v_fmac_f32_e32 v81, v82, v77
	v_fma_f32 v49, -v49, v81, v80
	v_div_fmas_f32 v49, v49, v77, v81
	v_div_fixup_f32 v78, v49, v78, 1.0
	v_mul_f32_e32 v49, 0x3d372713, v36
	v_mul_f32_e32 v49, v36, v49
	v_fma_f32 v49, v36, v49, v36
	v_mul_f32_e32 v49, 0x3fcc422a, v49
	v_mul_f32_e32 v49, 0xbfb8aa3b, v49
	v_pk_mul_f32 v[72:73], v[72:73], v[78:79]
	v_exp_f32_e32 v78, v49
	v_mul_f32_e32 v49, 0x3d372713, v38
	v_mul_f32_e32 v49, v38, v49
	v_fma_f32 v49, v38, v49, v38
	v_mul_f32_e32 v49, 0x3fcc422a, v49
	v_mul_f32_e32 v49, 0xbfb8aa3b, v49
	v_exp_f32_e32 v80, v49
	v_mul_f32_e32 v49, 0x3d372713, v37
	v_mul_f32_e32 v49, v37, v49
	v_fma_f32 v49, v37, v49, v37
	v_mul_f32_e32 v49, 0x3fcc422a, v49
	v_mul_f32_e32 v49, 0xbfb8aa3b, v49
	v_exp_f32_e32 v79, v49
	s_nop 0
	v_pk_add_f32 v[78:79], v[78:79], 1.0 op_sel_hi:[1,0]
	s_nop 0
	v_div_scale_f32 v49, s[66:67], v79, v79, 1.0
	v_rcp_f32_e32 v77, v49
	s_nop 0
	v_fma_f32 v81, -v49, v77, 1.0
	v_fmac_f32_e32 v77, v81, v77
	v_div_scale_f32 v81, vcc, 1.0, v79, 1.0
	v_mul_f32_e32 v82, v81, v77
	v_fma_f32 v83, -v49, v82, v81
	v_fmac_f32_e32 v82, v83, v77
	v_fma_f32 v49, -v49, v82, v81
	v_div_fmas_f32 v49, v49, v77, v82
	v_div_fixup_f32 v79, v49, v79, 1.0
	v_div_scale_f32 v49, s[66:67], v78, v78, 1.0
	v_rcp_f32_e32 v77, v49
	s_nop 0
	v_fma_f32 v81, -v49, v77, 1.0
	v_fmac_f32_e32 v77, v81, v77
	v_div_scale_f32 v81, vcc, 1.0, v78, 1.0
	v_mul_f32_e32 v82, v81, v77
	v_fma_f32 v83, -v49, v82, v81
	v_fmac_f32_e32 v82, v83, v77
	v_fma_f32 v49, -v49, v82, v81
	v_div_fmas_f32 v49, v49, v77, v82
	v_div_fixup_f32 v78, v49, v78, 1.0
	v_mul_f32_e32 v49, 0x3d372713, v39
	v_mul_f32_e32 v49, v39, v49
	v_fma_f32 v49, v39, v49, v39
	v_mul_f32_e32 v49, 0x3fcc422a, v49
	v_mul_f32_e32 v49, 0xbfb8aa3b, v49
	v_exp_f32_e32 v81, v49
	v_pk_mul_f32 v[36:37], v[36:37], v[78:79]
	v_pk_add_f32 v[78:79], v[80:81], 1.0 op_sel_hi:[1,0]
	s_nop 0
	v_div_scale_f32 v49, s[66:67], v79, v79, 1.0
	v_rcp_f32_e32 v77, v49
	v_cvt_pk_bf16_f32 v35, v36, v37
	v_cvt_pk_bf16_f32 v36, v72, v73
	v_lshl_add_u64 v[72:73], s[72:73], 0, v[58:59]
	v_fma_f32 v80, -v49, v77, 1.0
	v_fmac_f32_e32 v77, v80, v77
	v_div_scale_f32 v80, vcc, 1.0, v79, 1.0
	v_mul_f32_e32 v81, v80, v77
	v_fma_f32 v82, -v49, v81, v80
	v_fmac_f32_e32 v81, v82, v77
	v_fma_f32 v49, -v49, v81, v80
	v_div_fmas_f32 v49, v49, v77, v81
	v_div_fixup_f32 v79, v49, v79, 1.0
	v_div_scale_f32 v49, s[66:67], v78, v78, 1.0
	v_rcp_f32_e32 v77, v49
	v_lshl_add_u64 v[58:59], v[58:59], 0, s[56:57]
	v_fma_f32 v80, -v49, v77, 1.0
	v_fmac_f32_e32 v77, v80, v77
	v_div_scale_f32 v80, vcc, 1.0, v78, 1.0
	v_mul_f32_e32 v81, v80, v77
	v_fma_f32 v82, -v49, v81, v80
	v_fmac_f32_e32 v81, v82, v77
	v_fma_f32 v49, -v49, v81, v80
	v_div_fmas_f32 v49, v49, v77, v81
	v_div_fixup_f32 v78, v49, v78, 1.0
	v_pk_mul_f32 v[38:39], v[38:39], v[78:79]
	global_load_dwordx4 v[78:81], v[72:73], off offset:-64
	v_cvt_pk_bf16_f32 v37, v38, v39
	v_lshl_add_u64 v[38:39], s[72:73], 0, v[56:57]
	v_lshl_add_u64 v[56:57], v[56:57], 0, s[56:57]
	global_load_dwordx4 v[140:143], v[38:39], off offset:-64
	s_waitcnt vmcnt(1)
	v_mfma_f32_32x32x16_bf16 v[2:17], v[78:81], v[34:37], v[2:17]
	s_waitcnt vmcnt(0)
	v_mfma_f32_32x32x16_bf16 v[18:33], v[140:143], v[34:37], v[18:33]
	v_lshl_add_u64 v[78:79], v[66:67], 0, s[14:15]
	global_load_dwordx4 v[34:37], v[68:69], off offset:64
	s_nop 0
	global_load_dwordx4 v[78:81], v[78:79], off offset:16
	s_nop 0
	global_load_dwordx4 v[82:85], v[70:71], off offset:64
	s_nop 0
	global_load_dwordx4 v[86:89], v[86:87], off offset:16
	s_waitcnt vmcnt(1)
	v_pk_add_f32 v[84:85], v[36:37], v[84:85]
	s_waitcnt vmcnt(0)
	v_pk_add_f32 v[86:87], v[78:79], v[86:87]
	v_lshl_add_u64 v[78:79], v[40:41], 0, s[18:19]
	v_pk_add_f32 v[82:83], v[34:35], v[82:83]
	v_pk_add_f32 v[88:89], v[80:81], v[88:89]
	global_load_dwordx4 v[34:37], v[64:65], off offset:64
	s_nop 0
	global_load_dwordx4 v[78:81], v[78:79], off offset:16
	s_waitcnt vmcnt(1)
	v_pk_add_f32 v[84:85], v[84:85], v[36:37]
	s_waitcnt vmcnt(0)
	v_pk_add_f32 v[86:87], v[86:87], v[78:79]
	v_lshl_add_u64 v[78:79], v[40:41], 0, s[20:21]
	v_pk_add_f32 v[82:83], v[82:83], v[34:35]
	v_pk_add_f32 v[88:89], v[88:89], v[80:81]
	global_load_dwordx4 v[34:37], v[62:63], off offset:64
	s_nop 0
	global_load_dwordx4 v[78:81], v[78:79], off offset:16
	s_waitcnt vmcnt(1)
	v_pk_add_f32 v[84:85], v[84:85], v[36:37]
	s_waitcnt vmcnt(0)
	v_pk_add_f32 v[86:87], v[86:87], v[78:79]
	v_lshl_add_u64 v[78:79], v[40:41], 0, s[22:23]
	v_pk_add_f32 v[82:83], v[82:83], v[34:35]
	v_pk_add_f32 v[88:89], v[88:89], v[80:81]
	global_load_dwordx4 v[34:37], v[60:61], off offset:64
	s_nop 0
	global_load_dwordx4 v[78:81], v[78:79], off offset:16
	s_waitcnt vmcnt(1)
	v_pk_add_f32 v[34:35], v[82:83], v[34:35]
	s_nop 0
	v_mul_f32_e32 v49, 0x3d372713, v34
	v_mul_f32_e32 v49, v34, v49
	v_fma_f32 v49, v34, v49, v34
	v_mul_f32_e32 v49, 0x3fcc422a, v49
	s_waitcnt vmcnt(0)
	v_pk_add_f32 v[78:79], v[86:87], v[78:79]
	v_mul_f32_e32 v49, 0xbfb8aa3b, v49
	v_exp_f32_e32 v82, v49
	v_mul_f32_e32 v49, 0x3d372713, v78
	v_mul_f32_e32 v49, v78, v49
	v_fma_f32 v49, v78, v49, v78
	v_mul_f32_e32 v49, 0x3fcc422a, v49
	v_mul_f32_e32 v49, 0xbfb8aa3b, v49
	v_pk_add_f32 v[36:37], v[84:85], v[36:37]
	v_exp_f32_e32 v84, v49
	v_mul_f32_e32 v49, 0x3d372713, v35
	v_mul_f32_e32 v49, v35, v49
	v_fma_f32 v49, v35, v49, v35
	v_mul_f32_e32 v49, 0x3fcc422a, v49
	v_mul_f32_e32 v49, 0xbfb8aa3b, v49
	v_exp_f32_e32 v83, v49
	v_pk_add_f32 v[80:81], v[88:89], v[80:81]
	v_pk_add_f32 v[82:83], v[82:83], 1.0 op_sel_hi:[1,0]
	s_nop 0
	v_div_scale_f32 v49, s[66:67], v83, v83, 1.0
	v_rcp_f32_e32 v77, v49
	s_nop 0
	v_fma_f32 v85, -v49, v77, 1.0
	v_fmac_f32_e32 v77, v85, v77
	v_div_scale_f32 v85, vcc, 1.0, v83, 1.0
	v_mul_f32_e32 v86, v85, v77
	v_fma_f32 v87, -v49, v86, v85
	v_fmac_f32_e32 v86, v87, v77
	v_fma_f32 v49, -v49, v86, v85
	v_div_fmas_f32 v49, v49, v77, v86
	v_div_fixup_f32 v83, v49, v83, 1.0
	v_div_scale_f32 v49, s[66:67], v82, v82, 1.0
	v_rcp_f32_e32 v77, v49
	s_nop 0
	v_fma_f32 v85, -v49, v77, 1.0
	v_fmac_f32_e32 v77, v85, v77
	v_div_scale_f32 v85, vcc, 1.0, v82, 1.0
	v_mul_f32_e32 v86, v85, v77
	v_fma_f32 v87, -v49, v86, v85
	v_fmac_f32_e32 v86, v87, v77
	v_fma_f32 v49, -v49, v86, v85
	v_div_fmas_f32 v49, v49, v77, v86
	v_div_fixup_f32 v82, v49, v82, 1.0
	v_mul_f32_e32 v49, 0x3d372713, v79
	v_mul_f32_e32 v49, v79, v49
	v_fma_f32 v49, v79, v49, v79
	v_mul_f32_e32 v49, 0x3fcc422a, v49
	v_mul_f32_e32 v49, 0xbfb8aa3b, v49
	v_exp_f32_e32 v85, v49
	v_pk_mul_f32 v[34:35], v[34:35], v[82:83]
	v_pk_add_f32 v[82:83], v[84:85], 1.0 op_sel_hi:[1,0]
	s_nop 0
	v_div_scale_f32 v49, s[66:67], v83, v83, 1.0
	v_rcp_f32_e32 v77, v49
	v_cvt_pk_bf16_f32 v34, v34, v35
	v_fma_f32 v84, -v49, v77, 1.0
	v_fmac_f32_e32 v77, v84, v77
	v_div_scale_f32 v84, vcc, 1.0, v83, 1.0
	v_mul_f32_e32 v85, v84, v77
	v_fma_f32 v86, -v49, v85, v84
	v_fmac_f32_e32 v85, v86, v77
	v_fma_f32 v49, -v49, v85, v84
	v_div_fmas_f32 v49, v49, v77, v85
	v_div_fixup_f32 v83, v49, v83, 1.0
	v_div_scale_f32 v49, s[66:67], v82, v82, 1.0
	v_rcp_f32_e32 v77, v49
	s_nop 0
	v_fma_f32 v84, -v49, v77, 1.0
	v_fmac_f32_e32 v77, v84, v77
	v_div_scale_f32 v84, vcc, 1.0, v82, 1.0
	v_mul_f32_e32 v85, v84, v77
	v_fma_f32 v86, -v49, v85, v84
	v_fmac_f32_e32 v85, v86, v77
	v_fma_f32 v49, -v49, v85, v84
	v_div_fmas_f32 v49, v49, v77, v85
	v_div_fixup_f32 v82, v49, v82, 1.0
	v_mul_f32_e32 v49, 0x3d372713, v36
	v_mul_f32_e32 v49, v36, v49
	v_fma_f32 v49, v36, v49, v36
	v_mul_f32_e32 v49, 0x3fcc422a, v49
	v_mul_f32_e32 v49, 0xbfb8aa3b, v49
	v_pk_mul_f32 v[78:79], v[78:79], v[82:83]
	v_exp_f32_e32 v82, v49
	v_mul_f32_e32 v49, 0x3d372713, v80
	v_mul_f32_e32 v49, v80, v49
	v_fma_f32 v49, v80, v49, v80
	v_mul_f32_e32 v49, 0x3fcc422a, v49
	v_mul_f32_e32 v49, 0xbfb8aa3b, v49
	v_exp_f32_e32 v84, v49
	v_mul_f32_e32 v49, 0x3d372713, v37
	v_mul_f32_e32 v49, v37, v49
	v_fma_f32 v49, v37, v49, v37
	v_mul_f32_e32 v49, 0x3fcc422a, v49
	v_mul_f32_e32 v49, 0xbfb8aa3b, v49
	v_exp_f32_e32 v83, v49
	s_nop 0
	v_pk_add_f32 v[82:83], v[82:83], 1.0 op_sel_hi:[1,0]
	s_nop 0
	v_div_scale_f32 v49, s[66:67], v83, v83, 1.0
	v_rcp_f32_e32 v77, v49
	s_nop 0
	v_fma_f32 v85, -v49, v77, 1.0
	v_fmac_f32_e32 v77, v85, v77
	v_div_scale_f32 v85, vcc, 1.0, v83, 1.0
	v_mul_f32_e32 v86, v85, v77
	v_fma_f32 v87, -v49, v86, v85
	v_fmac_f32_e32 v86, v87, v77
	v_fma_f32 v49, -v49, v86, v85
	v_div_fmas_f32 v49, v49, v77, v86
	v_div_fixup_f32 v83, v49, v83, 1.0
	v_div_scale_f32 v49, s[66:67], v82, v82, 1.0
	v_rcp_f32_e32 v77, v49
	s_nop 0
	v_fma_f32 v85, -v49, v77, 1.0
	v_fmac_f32_e32 v77, v85, v77
	v_div_scale_f32 v85, vcc, 1.0, v82, 1.0
	v_mul_f32_e32 v86, v85, v77
	v_fma_f32 v87, -v49, v86, v85
	v_fmac_f32_e32 v86, v87, v77
	v_fma_f32 v49, -v49, v86, v85
	v_div_fmas_f32 v49, v49, v77, v86
	v_div_fixup_f32 v82, v49, v82, 1.0
	v_mul_f32_e32 v49, 0x3d372713, v81
	v_mul_f32_e32 v49, v81, v49
	v_fma_f32 v49, v81, v49, v81
	v_mul_f32_e32 v49, 0x3fcc422a, v49
	v_mul_f32_e32 v49, 0xbfb8aa3b, v49
	v_exp_f32_e32 v85, v49
	v_pk_mul_f32 v[36:37], v[36:37], v[82:83]
	v_pk_add_f32 v[82:83], v[84:85], 1.0 op_sel_hi:[1,0]
	s_nop 0
	v_div_scale_f32 v49, s[66:67], v83, v83, 1.0
	v_rcp_f32_e32 v77, v49
	v_cvt_pk_bf16_f32 v35, v36, v37
	v_cvt_pk_bf16_f32 v36, v78, v79
	v_fma_f32 v84, -v49, v77, 1.0
	v_fmac_f32_e32 v77, v84, v77
	v_div_scale_f32 v84, vcc, 1.0, v83, 1.0
	v_mul_f32_e32 v85, v84, v77
	v_fma_f32 v86, -v49, v85, v84
	v_fmac_f32_e32 v85, v86, v77
	v_fma_f32 v49, -v49, v85, v84
	v_div_fmas_f32 v49, v49, v77, v85
	v_div_fixup_f32 v83, v49, v83, 1.0
	v_div_scale_f32 v49, s[66:67], v82, v82, 1.0
	v_rcp_f32_e32 v77, v49
	s_nop 0
	v_fma_f32 v84, -v49, v77, 1.0
	v_fmac_f32_e32 v77, v84, v77
	v_div_scale_f32 v84, vcc, 1.0, v82, 1.0
	v_mul_f32_e32 v85, v84, v77
	v_fma_f32 v86, -v49, v85, v84
	v_fmac_f32_e32 v85, v86, v77
	v_fma_f32 v49, -v49, v85, v84
	v_div_fmas_f32 v49, v49, v77, v85
	v_div_fixup_f32 v82, v49, v82, 1.0
	v_pk_mul_f32 v[80:81], v[80:81], v[82:83]
	v_lshl_add_u64 v[86:87], v[40:41], 0, s[26:27]
	v_cvt_pk_bf16_f32 v37, v80, v81
	global_load_dwordx4 v[78:81], v[72:73], off offset:-32
	global_load_dwordx4 v[140:143], v[38:39], off offset:-32
	s_waitcnt vmcnt(1)
	v_mfma_f32_32x32x16_bf16 v[2:17], v[78:81], v[34:37], v[2:17]
	s_waitcnt vmcnt(0)
	v_mfma_f32_32x32x16_bf16 v[18:33], v[140:143], v[34:37], v[18:33]
	v_lshl_add_u64 v[78:79], v[66:67], 0, s[24:25]
	global_load_dwordx4 v[34:37], v[68:69], off offset:128
	s_nop 0
	global_load_dwordx4 v[78:81], v[78:79], off offset:16
	s_nop 0
	global_load_dwordx4 v[82:85], v[70:71], off offset:128
	s_nop 0
	global_load_dwordx4 v[86:89], v[86:87], off offset:16
	v_lshl_add_u64 v[66:67], v[66:67], 0, s[36:37]
	s_waitcnt vmcnt(1)
	v_pk_add_f32 v[84:85], v[36:37], v[84:85]
	s_waitcnt vmcnt(0)
	v_pk_add_f32 v[86:87], v[78:79], v[86:87]
	v_lshl_add_u64 v[78:79], v[40:41], 0, s[28:29]
	v_pk_add_f32 v[82:83], v[34:35], v[82:83]
	v_pk_add_f32 v[88:89], v[80:81], v[88:89]
	global_load_dwordx4 v[34:37], v[64:65], off offset:128
	s_nop 0
	global_load_dwordx4 v[78:81], v[78:79], off offset:16
	s_waitcnt vmcnt(1)
	v_pk_add_f32 v[84:85], v[84:85], v[36:37]
	s_waitcnt vmcnt(0)
	v_pk_add_f32 v[86:87], v[86:87], v[78:79]
	v_lshl_add_u64 v[78:79], v[40:41], 0, s[30:31]
	v_pk_add_f32 v[82:83], v[82:83], v[34:35]
	v_pk_add_f32 v[88:89], v[88:89], v[80:81]
	global_load_dwordx4 v[34:37], v[62:63], off offset:128
	s_nop 0
	global_load_dwordx4 v[78:81], v[78:79], off offset:16
	s_waitcnt vmcnt(1)
	v_pk_add_f32 v[84:85], v[84:85], v[36:37]
	s_waitcnt vmcnt(0)
	v_pk_add_f32 v[86:87], v[86:87], v[78:79]
	v_lshl_add_u64 v[78:79], v[40:41], 0, s[34:35]
	v_pk_add_f32 v[82:83], v[82:83], v[34:35]
	v_pk_add_f32 v[88:89], v[88:89], v[80:81]
	global_load_dwordx4 v[34:37], v[60:61], off offset:128
	s_nop 0
	global_load_dwordx4 v[78:81], v[78:79], off offset:16
	s_waitcnt vmcnt(1)
	v_pk_add_f32 v[34:35], v[82:83], v[34:35]
	s_nop 0
	v_mul_f32_e32 v49, 0x3d372713, v34
	v_mul_f32_e32 v49, v34, v49
	v_fma_f32 v49, v34, v49, v34
	v_mul_f32_e32 v49, 0x3fcc422a, v49
	s_waitcnt vmcnt(0)
	v_pk_add_f32 v[78:79], v[86:87], v[78:79]
	v_mul_f32_e32 v49, 0xbfb8aa3b, v49
	v_exp_f32_e32 v82, v49
	v_mul_f32_e32 v49, 0x3d372713, v78
	v_mul_f32_e32 v49, v78, v49
	v_fma_f32 v49, v78, v49, v78
	v_mul_f32_e32 v49, 0x3fcc422a, v49
	v_mul_f32_e32 v49, 0xbfb8aa3b, v49
	v_pk_add_f32 v[36:37], v[84:85], v[36:37]
	v_exp_f32_e32 v84, v49
	v_mul_f32_e32 v49, 0x3d372713, v35
	v_mul_f32_e32 v49, v35, v49
	v_fma_f32 v49, v35, v49, v35
	v_mul_f32_e32 v49, 0x3fcc422a, v49
	v_mul_f32_e32 v49, 0xbfb8aa3b, v49
	v_exp_f32_e32 v83, v49
	v_pk_add_f32 v[80:81], v[88:89], v[80:81]
	v_pk_add_f32 v[82:83], v[82:83], 1.0 op_sel_hi:[1,0]
	s_nop 0
	v_div_scale_f32 v49, s[66:67], v83, v83, 1.0
	v_rcp_f32_e32 v77, v49
	s_nop 0
	v_fma_f32 v85, -v49, v77, 1.0
	v_fmac_f32_e32 v77, v85, v77
	v_div_scale_f32 v85, vcc, 1.0, v83, 1.0
	v_mul_f32_e32 v86, v85, v77
	v_fma_f32 v87, -v49, v86, v85
	v_fmac_f32_e32 v86, v87, v77
	v_fma_f32 v49, -v49, v86, v85
	v_div_fmas_f32 v49, v49, v77, v86
	v_div_fixup_f32 v83, v49, v83, 1.0
	v_div_scale_f32 v49, s[66:67], v82, v82, 1.0
	v_rcp_f32_e32 v77, v49
	s_nop 0
	v_fma_f32 v85, -v49, v77, 1.0
	v_fmac_f32_e32 v77, v85, v77
	v_div_scale_f32 v85, vcc, 1.0, v82, 1.0
	v_mul_f32_e32 v86, v85, v77
	v_fma_f32 v87, -v49, v86, v85
	v_fmac_f32_e32 v86, v87, v77
	v_fma_f32 v49, -v49, v86, v85
	v_div_fmas_f32 v49, v49, v77, v86
	v_div_fixup_f32 v82, v49, v82, 1.0
	v_mul_f32_e32 v49, 0x3d372713, v79
	v_mul_f32_e32 v49, v79, v49
	v_fma_f32 v49, v79, v49, v79
	v_mul_f32_e32 v49, 0x3fcc422a, v49
	v_mul_f32_e32 v49, 0xbfb8aa3b, v49
	v_exp_f32_e32 v85, v49
	v_pk_mul_f32 v[34:35], v[34:35], v[82:83]
	v_pk_add_f32 v[82:83], v[84:85], 1.0 op_sel_hi:[1,0]
	s_nop 0
	v_div_scale_f32 v49, s[66:67], v83, v83, 1.0
	v_rcp_f32_e32 v77, v49
	v_cvt_pk_bf16_f32 v34, v34, v35
	v_fma_f32 v84, -v49, v77, 1.0
	v_fmac_f32_e32 v77, v84, v77
	v_div_scale_f32 v84, vcc, 1.0, v83, 1.0
	v_mul_f32_e32 v85, v84, v77
	v_fma_f32 v86, -v49, v85, v84
	v_fmac_f32_e32 v85, v86, v77
	v_fma_f32 v49, -v49, v85, v84
	v_div_fmas_f32 v49, v49, v77, v85
	v_div_fixup_f32 v83, v49, v83, 1.0
	v_div_scale_f32 v49, s[66:67], v82, v82, 1.0
	v_rcp_f32_e32 v77, v49
	s_nop 0
	v_fma_f32 v84, -v49, v77, 1.0
	v_fmac_f32_e32 v77, v84, v77
	v_div_scale_f32 v84, vcc, 1.0, v82, 1.0
	v_mul_f32_e32 v85, v84, v77
	v_fma_f32 v86, -v49, v85, v84
	v_fmac_f32_e32 v85, v86, v77
	v_fma_f32 v49, -v49, v85, v84
	v_div_fmas_f32 v49, v49, v77, v85
	v_div_fixup_f32 v82, v49, v82, 1.0
	v_mul_f32_e32 v49, 0x3d372713, v36
	v_mul_f32_e32 v49, v36, v49
	v_fma_f32 v49, v36, v49, v36
	v_mul_f32_e32 v49, 0x3fcc422a, v49
	v_mul_f32_e32 v49, 0xbfb8aa3b, v49
	v_pk_mul_f32 v[78:79], v[78:79], v[82:83]
	v_exp_f32_e32 v82, v49
	v_mul_f32_e32 v49, 0x3d372713, v80
	v_mul_f32_e32 v49, v80, v49
	v_fma_f32 v49, v80, v49, v80
	v_mul_f32_e32 v49, 0x3fcc422a, v49
	v_mul_f32_e32 v49, 0xbfb8aa3b, v49
	v_exp_f32_e32 v84, v49
	v_mul_f32_e32 v49, 0x3d372713, v37
	v_mul_f32_e32 v49, v37, v49
	v_fma_f32 v49, v37, v49, v37
	v_mul_f32_e32 v49, 0x3fcc422a, v49
	v_mul_f32_e32 v49, 0xbfb8aa3b, v49
	v_exp_f32_e32 v83, v49
	s_nop 0
	v_pk_add_f32 v[82:83], v[82:83], 1.0 op_sel_hi:[1,0]
	s_nop 0
	v_div_scale_f32 v49, s[66:67], v83, v83, 1.0
	v_rcp_f32_e32 v77, v49
	s_nop 0
	v_fma_f32 v85, -v49, v77, 1.0
	v_fmac_f32_e32 v77, v85, v77
	v_div_scale_f32 v85, vcc, 1.0, v83, 1.0
	v_mul_f32_e32 v86, v85, v77
	v_fma_f32 v87, -v49, v86, v85
	v_fmac_f32_e32 v86, v87, v77
	v_fma_f32 v49, -v49, v86, v85
	v_div_fmas_f32 v49, v49, v77, v86
	v_div_fixup_f32 v83, v49, v83, 1.0
	v_div_scale_f32 v49, s[66:67], v82, v82, 1.0
	v_rcp_f32_e32 v77, v49
	s_nop 0
	v_fma_f32 v85, -v49, v77, 1.0
	v_fmac_f32_e32 v77, v85, v77
	v_div_scale_f32 v85, vcc, 1.0, v82, 1.0
	v_mul_f32_e32 v86, v85, v77
	v_fma_f32 v87, -v49, v86, v85
	v_fmac_f32_e32 v86, v87, v77
	v_fma_f32 v49, -v49, v86, v85
	v_div_fmas_f32 v49, v49, v77, v86
	v_div_fixup_f32 v82, v49, v82, 1.0
	v_mul_f32_e32 v49, 0x3d372713, v81
	v_mul_f32_e32 v49, v81, v49
	v_fma_f32 v49, v81, v49, v81
	v_mul_f32_e32 v49, 0x3fcc422a, v49
	v_mul_f32_e32 v49, 0xbfb8aa3b, v49
	v_exp_f32_e32 v85, v49
	v_pk_mul_f32 v[36:37], v[36:37], v[82:83]
	v_pk_add_f32 v[82:83], v[84:85], 1.0 op_sel_hi:[1,0]
	s_nop 0
	v_div_scale_f32 v49, s[66:67], v83, v83, 1.0
	v_rcp_f32_e32 v77, v49
	v_cvt_pk_bf16_f32 v35, v36, v37
	v_cvt_pk_bf16_f32 v36, v78, v79
	v_fma_f32 v84, -v49, v77, 1.0
	v_fmac_f32_e32 v77, v84, v77
	v_div_scale_f32 v84, vcc, 1.0, v83, 1.0
	v_mul_f32_e32 v85, v84, v77
	v_fma_f32 v86, -v49, v85, v84
	v_fmac_f32_e32 v85, v86, v77
	v_fma_f32 v49, -v49, v85, v84
	v_div_fmas_f32 v49, v49, v77, v85
	v_div_fixup_f32 v83, v49, v83, 1.0
	v_div_scale_f32 v49, s[66:67], v82, v82, 1.0
	v_rcp_f32_e32 v77, v49
	s_nop 0
	v_fma_f32 v84, -v49, v77, 1.0
	v_fmac_f32_e32 v77, v84, v77
	v_div_scale_f32 v84, vcc, 1.0, v82, 1.0
	v_mul_f32_e32 v85, v84, v77
	v_fma_f32 v86, -v49, v85, v84
	v_fmac_f32_e32 v85, v86, v77
	v_fma_f32 v49, -v49, v85, v84
	v_div_fmas_f32 v49, v49, v77, v85
	v_div_fixup_f32 v82, v49, v82, 1.0
	v_pk_mul_f32 v[80:81], v[80:81], v[82:83]
	v_lshl_add_u64 v[82:83], v[40:41], 0, s[40:41]
	v_cvt_pk_bf16_f32 v37, v80, v81
	global_load_dwordx4 v[78:81], v[72:73], off
	global_load_dwordx4 v[140:143], v[38:39], off
	s_waitcnt vmcnt(1)
	v_mfma_f32_32x32x16_bf16 v[2:17], v[78:81], v[34:37], v[2:17]
	s_waitcnt vmcnt(0)
	v_mfma_f32_32x32x16_bf16 v[18:33], v[140:143], v[34:37], v[18:33]
	global_load_dwordx4 v[34:37], v[68:69], off offset:192
	s_nop 0
	global_load_dwordx4 v[66:69], v[66:67], off offset:16
	s_nop 0
	global_load_dwordx4 v[78:81], v[70:71], off offset:192
	s_nop 0
	global_load_dwordx4 v[82:85], v[82:83], off offset:16
	s_waitcnt vmcnt(1)
	v_pk_add_f32 v[70:71], v[36:37], v[80:81]
	s_waitcnt vmcnt(0)
	v_pk_add_f32 v[80:81], v[66:67], v[82:83]
	v_lshl_add_u64 v[66:67], v[40:41], 0, s[46:47]
	v_pk_add_f32 v[78:79], v[34:35], v[78:79]
	global_load_dwordx4 v[34:37], v[64:65], off offset:192
	s_nop 0
	global_load_dwordx4 v[64:67], v[66:67], off offset:16
	v_pk_add_f32 v[68:69], v[68:69], v[84:85]
	s_waitcnt vmcnt(1)
	v_pk_add_f32 v[70:71], v[70:71], v[36:37]
	s_waitcnt vmcnt(0)
	v_pk_add_f32 v[66:67], v[68:69], v[66:67]
	v_pk_add_f32 v[68:69], v[80:81], v[64:65]
	v_lshl_add_u64 v[64:65], v[40:41], 0, s[50:51]
	v_pk_add_f32 v[78:79], v[78:79], v[34:35]
	global_load_dwordx4 v[34:37], v[62:63], off offset:192
	s_nop 0
	global_load_dwordx4 v[62:65], v[64:65], off offset:16
	v_lshl_add_u64 v[40:41], v[40:41], 0, s[52:53]
	s_waitcnt vmcnt(1)
	v_pk_add_f32 v[70:71], v[70:71], v[36:37]
	v_pk_add_f32 v[78:79], v[78:79], v[34:35]
	s_waitcnt vmcnt(0)
	v_pk_add_f32 v[64:65], v[66:67], v[64:65]
	v_pk_add_f32 v[66:67], v[68:69], v[62:63]
	global_load_dwordx4 v[34:37], v[60:61], off offset:192
	s_nop 0
	global_load_dwordx4 v[60:63], v[40:41], off offset:16
	s_waitcnt vmcnt(1)
	v_pk_add_f32 v[34:35], v[78:79], v[34:35]
	s_nop 0
	v_mul_f32_e32 v49, 0x3d372713, v34
	v_mul_f32_e32 v49, v34, v49
	v_fma_f32 v49, v34, v49, v34
	v_mul_f32_e32 v49, 0x3fcc422a, v49
	s_waitcnt vmcnt(0)
	v_pk_add_f32 v[60:61], v[66:67], v[60:61]
	v_mul_f32_e32 v49, 0xbfb8aa3b, v49
	v_pk_add_f32 v[40:41], v[64:65], v[62:63]
	v_exp_f32_e32 v62, v49
	v_mul_f32_e32 v49, 0x3d372713, v60
	v_mul_f32_e32 v49, v60, v49
	v_fma_f32 v49, v60, v49, v60
	v_mul_f32_e32 v49, 0x3fcc422a, v49
	v_mul_f32_e32 v49, 0xbfb8aa3b, v49
	v_exp_f32_e32 v64, v49
	v_mul_f32_e32 v49, 0x3d372713, v35
	v_mul_f32_e32 v49, v35, v49
	v_fma_f32 v49, v35, v49, v35
	v_mul_f32_e32 v49, 0x3fcc422a, v49
	v_mul_f32_e32 v49, 0xbfb8aa3b, v49
	v_exp_f32_e32 v63, v49
	v_pk_add_f32 v[36:37], v[70:71], v[36:37]
	v_pk_add_f32 v[62:63], v[62:63], 1.0 op_sel_hi:[1,0]
	s_nop 0
	v_div_scale_f32 v49, s[66:67], v63, v63, 1.0
	v_rcp_f32_e32 v65, v49
	s_nop 0
	v_fma_f32 v66, -v49, v65, 1.0
	v_fmac_f32_e32 v65, v66, v65
	v_div_scale_f32 v66, vcc, 1.0, v63, 1.0
	v_mul_f32_e32 v67, v66, v65
	v_fma_f32 v68, -v49, v67, v66
	v_fmac_f32_e32 v67, v68, v65
	v_fma_f32 v49, -v49, v67, v66
	v_div_fmas_f32 v49, v49, v65, v67
	v_div_fixup_f32 v63, v49, v63, 1.0
	v_div_scale_f32 v49, s[66:67], v62, v62, 1.0
	v_rcp_f32_e32 v65, v49
	s_nop 0
	v_fma_f32 v66, -v49, v65, 1.0
	v_fmac_f32_e32 v65, v66, v65
	v_div_scale_f32 v66, vcc, 1.0, v62, 1.0
	v_mul_f32_e32 v67, v66, v65
	v_fma_f32 v68, -v49, v67, v66
	v_fmac_f32_e32 v67, v68, v65
	v_fma_f32 v49, -v49, v67, v66
	v_div_fmas_f32 v49, v49, v65, v67
	v_div_fixup_f32 v62, v49, v62, 1.0
	v_mul_f32_e32 v49, 0x3d372713, v61
	v_mul_f32_e32 v49, v61, v49
	v_fma_f32 v49, v61, v49, v61
	v_mul_f32_e32 v49, 0x3fcc422a, v49
	v_mul_f32_e32 v49, 0xbfb8aa3b, v49
	v_exp_f32_e32 v65, v49
	v_pk_mul_f32 v[34:35], v[34:35], v[62:63]
	v_pk_add_f32 v[62:63], v[64:65], 1.0 op_sel_hi:[1,0]
	s_nop 0
	v_div_scale_f32 v49, s[66:67], v63, v63, 1.0
	v_rcp_f32_e32 v64, v49
	v_cvt_pk_bf16_f32 v34, v34, v35
	v_fma_f32 v65, -v49, v64, 1.0
	v_fmac_f32_e32 v64, v65, v64
	v_div_scale_f32 v65, vcc, 1.0, v63, 1.0
	v_mul_f32_e32 v66, v65, v64
	v_fma_f32 v67, -v49, v66, v65
	v_fmac_f32_e32 v66, v67, v64
	v_fma_f32 v49, -v49, v66, v65
	v_div_fmas_f32 v49, v49, v64, v66
	v_div_fixup_f32 v63, v49, v63, 1.0
	v_div_scale_f32 v49, s[66:67], v62, v62, 1.0
	v_rcp_f32_e32 v64, v49
	s_nop 0
	v_fma_f32 v65, -v49, v64, 1.0
	v_fmac_f32_e32 v64, v65, v64
	v_div_scale_f32 v65, vcc, 1.0, v62, 1.0
	v_mul_f32_e32 v66, v65, v64
	v_fma_f32 v67, -v49, v66, v65
	v_fmac_f32_e32 v66, v67, v64
	v_fma_f32 v49, -v49, v66, v65
	v_div_fmas_f32 v49, v49, v64, v66
	v_div_fixup_f32 v62, v49, v62, 1.0
	v_mul_f32_e32 v49, 0x3d372713, v36
	v_mul_f32_e32 v49, v36, v49
	v_fma_f32 v49, v36, v49, v36
	v_mul_f32_e32 v49, 0x3fcc422a, v49
	v_mul_f32_e32 v49, 0xbfb8aa3b, v49
	v_pk_mul_f32 v[60:61], v[60:61], v[62:63]
	v_exp_f32_e32 v62, v49
	v_mul_f32_e32 v49, 0x3d372713, v40
	v_mul_f32_e32 v49, v40, v49
	v_fma_f32 v49, v40, v49, v40
	v_mul_f32_e32 v49, 0x3fcc422a, v49
	v_mul_f32_e32 v49, 0xbfb8aa3b, v49
	v_exp_f32_e32 v64, v49
	v_mul_f32_e32 v49, 0x3d372713, v37
	v_mul_f32_e32 v49, v37, v49
	v_fma_f32 v49, v37, v49, v37
	v_mul_f32_e32 v49, 0x3fcc422a, v49
	v_mul_f32_e32 v49, 0xbfb8aa3b, v49
	v_exp_f32_e32 v63, v49
	s_nop 0
	v_pk_add_f32 v[62:63], v[62:63], 1.0 op_sel_hi:[1,0]
	s_nop 0
	v_div_scale_f32 v49, s[66:67], v63, v63, 1.0
	v_rcp_f32_e32 v65, v49
	s_nop 0
	v_fma_f32 v66, -v49, v65, 1.0
	v_fmac_f32_e32 v65, v66, v65
	v_div_scale_f32 v66, vcc, 1.0, v63, 1.0
	v_mul_f32_e32 v67, v66, v65
	v_fma_f32 v68, -v49, v67, v66
	v_fmac_f32_e32 v67, v68, v65
	v_fma_f32 v49, -v49, v67, v66
	v_div_fmas_f32 v49, v49, v65, v67
	v_div_fixup_f32 v63, v49, v63, 1.0
	v_div_scale_f32 v49, s[66:67], v62, v62, 1.0
	v_rcp_f32_e32 v65, v49
	s_nop 0
	v_fma_f32 v66, -v49, v65, 1.0
	v_fmac_f32_e32 v65, v66, v65
	v_div_scale_f32 v66, vcc, 1.0, v62, 1.0
	v_mul_f32_e32 v67, v66, v65
	v_fma_f32 v68, -v49, v67, v66
	v_fmac_f32_e32 v67, v68, v65
	v_fma_f32 v49, -v49, v67, v66
	v_div_fmas_f32 v49, v49, v65, v67
	v_div_fixup_f32 v62, v49, v62, 1.0
	v_mul_f32_e32 v49, 0x3d372713, v41
	v_mul_f32_e32 v49, v41, v49
	v_fma_f32 v49, v41, v49, v41
	v_mul_f32_e32 v49, 0x3fcc422a, v49
	v_mul_f32_e32 v49, 0xbfb8aa3b, v49
	v_exp_f32_e32 v65, v49
	v_pk_mul_f32 v[36:37], v[36:37], v[62:63]
	v_pk_add_f32 v[62:63], v[64:65], 1.0 op_sel_hi:[1,0]
	s_nop 0
	v_div_scale_f32 v49, s[66:67], v63, v63, 1.0
	v_rcp_f32_e32 v64, v49
	v_cvt_pk_bf16_f32 v35, v36, v37
	v_cvt_pk_bf16_f32 v36, v60, v61
	v_fma_f32 v65, -v49, v64, 1.0
	v_fmac_f32_e32 v64, v65, v64
	v_div_scale_f32 v65, vcc, 1.0, v63, 1.0
	v_mul_f32_e32 v66, v65, v64
	v_fma_f32 v67, -v49, v66, v65
	v_fmac_f32_e32 v66, v67, v64
	v_fma_f32 v49, -v49, v66, v65
	v_div_fmas_f32 v49, v49, v64, v66
	v_div_fixup_f32 v63, v49, v63, 1.0
	v_div_scale_f32 v49, s[66:67], v62, v62, 1.0
	v_rcp_f32_e32 v64, v49
	s_nop 0
	v_fma_f32 v65, -v49, v64, 1.0
	v_fmac_f32_e32 v64, v65, v64
	v_div_scale_f32 v65, vcc, 1.0, v62, 1.0
	v_mul_f32_e32 v66, v65, v64
	v_fma_f32 v67, -v49, v66, v65
	v_fmac_f32_e32 v66, v67, v64
	v_fma_f32 v49, -v49, v66, v65
	v_div_fmas_f32 v49, v49, v64, v66
	v_div_fixup_f32 v62, v49, v62, 1.0
	v_pk_mul_f32 v[40:41], v[40:41], v[62:63]
	global_load_dwordx4 v[60:63], v[72:73], off offset:32
	v_cvt_pk_bf16_f32 v37, v40, v41
	global_load_dwordx4 v[38:41], v[38:39], off offset:32
	s_waitcnt vmcnt(1)
	v_mfma_f32_32x32x16_bf16 v[2:17], v[60:63], v[34:37], v[2:17]
	s_waitcnt vmcnt(0)
	v_mfma_f32_32x32x16_bf16 v[18:33], v[38:41], v[34:37], v[18:33]
	s_cbranch_scc0 .LBB0_1000
	v_lshlrev_b32_e32 v100, 4, v199
	s_cmp_eq_u32 s92, 0
	s_cbranch_scc1 .Lp8_w0
	s_add_i32 s96, s92, -1
	s_lshl_b32 s96, s96, 13
	v_add_u32_e32 v100, s96, v100
	s_nop 7
	s_nop 7
	ds_write_b128 v100, v[2:5]
	ds_write_b128 v100, v[6:9] offset:1024
	ds_write_b128 v100, v[10:13] offset:2048
	ds_write_b128 v100, v[14:17] offset:3072
	ds_write_b128 v100, v[18:21] offset:4096
	ds_write_b128 v100, v[22:25] offset:5120
	ds_write_b128 v100, v[26:29] offset:6144
	ds_write_b128 v100, v[30:33] offset:7168
	s_waitcnt lgkmcnt(0)
	s_barrier
	s_branch .LBB0_998
